# DSA attention: score scale 0.125 folded into the softmax exp2 constant (exact power-of-two), pbuf writes use immediate offsets from a per-token base
# baseline (speedup 1.0000x reference)
;   __device__ __forceinline__ half_t* mm() const { return (half_t*)(ws() + OFF_mm); }
; __device__ __forceinline__ void dsa_item(const KP& p, int b, int tile, char* smem) {
;     ...
;     const int nsel = min(cnt[tk], 256);
;     const half_t* urow = ub + (size_t)t * NU;
;     const int col = lane & 15;
;     h8 q0, q1;
; #pragma unroll
;     for (int e = 0; e < 8; ++e) { q0[e] = (half_t)0.f; q1[e] = (half_t)0.f; }
;     if (col < 8) {
;       q0 = *(const h8*)(urow + C_BQ + col * 64 + hq * 8);
;       q1 = *(const h8*)(urow + C_BQ + col * 64 + 32 + hq * 8);
;     }
;     float mx = NEGF;
; #pragma unroll 1
;     for (int mg = 0; mg < 2; ++mg) {
; #pragma unroll
;       for (int mm = 0; mm < 8; ++mm) {
;         const int m = mg * 8 + mm;
;         const int pos = m * 16 + col;
;         const int s = (pos < nsel) ? (int)sel[tk * 256 + pos] : 0;
;         const half_t* kp = ub + (size_t)s * NU + C_BK + hq * 8;
;         const h8 a0 = *(const h8*)kp, a1 = *(const h8*)(kp + 32);
.LBB0_1427:
	s_or_b64 exec, exec, s[2:3]
	s_waitcnt lgkmcnt(0)
	v_min_i32_e32 v85, 0x100, v11
	v_lshlrev_b32_e32 v14, 9, v10
	v_mov_b32_e32 v15, 0xf149f2ca
	s_add_u32 s14, s78, 0x3800
	s_addc_u32 s15, s79, 0
	v_add_u32_e32 v203, v126, v157
	v_lshl_add_u32 v80, v203, 1, v14
	ds_read_u16 v172, v80 offset:32768
	ds_read_u16 v173, v80 offset:32896
	ds_read_u16 v174, v80 offset:33024
	ds_read_u16 v175, v80 offset:33152
	v_and_b32_e32 v200, 7, v157
	v_lshlrev_b32_e32 v200, 4, v200
	v_mul_u32_u24_e32 v201, 0x240, v159
	v_add_u32_e32 v201, 0xa800, v201
	v_mul_u32_u24_e32 v198, 0x90, v165
	v_add3_u32 v198, v198, v200, v201
	v_mul_u32_u24_e32 v199, 0x90, v157
	v_add3_u32 v199, v199, v126, v201
	v_lshlrev_b32_e32 v202, 8, v159
	v_add_u32_e32 v202, 0xcc00, v202
	v_lshl_add_u32 v81, v203, 2, v202
	v_add_u32_e32 v171, -1, v85
	v_add_u32_e32 v156, -2, v85
	v_add_u32_e32 v158, -3, v85
	v_cmp_lt_i32_e32 vcc, v203, v85
	s_waitcnt lgkmcnt(3)
	s_nop 0
	v_cndmask_b32_e32 v172, 0, v172, vcc
	v_mul_u32_u24_e32 v172, 0x3a00, v172
	ds_write_b32 v81, v172
	v_add_u32_e32 v201, 64, v203
	v_cmp_lt_i32_e32 vcc, v201, v85
	s_waitcnt lgkmcnt(2)
	s_nop 0
	v_cndmask_b32_e32 v173, 0, v173, vcc
	v_mul_u32_u24_e32 v173, 0x3a00, v173
	ds_write_b32 v81, v173 offset:256
	v_add_u32_e32 v201, 0x80, v203
	v_cmp_lt_i32_e32 vcc, v201, v85
	s_waitcnt lgkmcnt(1)
	s_nop 0
	v_cndmask_b32_e32 v174, 0, v174, vcc
	v_mul_u32_u24_e32 v174, 0x3a00, v174
	ds_write_b32 v81, v174 offset:512
	v_add_u32_e32 v201, 0xc0, v203
	v_cmp_lt_i32_e32 vcc, v201, v85
	s_waitcnt lgkmcnt(0)
	s_nop 0
	v_cndmask_b32_e32 v175, 0, v175, vcc
	v_mul_u32_u24_e32 v175, 0x3a00, v175
	ds_write_b32 v81, v175 offset:768
	v_lshl_add_u32 v202, v165, 2, v202
	ds_read_b32 v172, v202
	ds_read_b32 v173, v202 offset:64
	ds_read_b32 v174, v202 offset:128
	ds_read_b32 v175, v202 offset:192
	ds_read_b32 v176, v202 offset:256
	ds_read_b32 v177, v202 offset:320
	ds_read_b32 v178, v202 offset:384
	ds_read_b32 v179, v202 offset:448
	ds_read_b32 v180, v202 offset:512
	ds_read_b32 v181, v202 offset:576
	ds_read_b32 v188, v202 offset:640
	ds_read_b32 v189, v202 offset:704
	ds_read_b32 v190, v202 offset:768
	ds_read_b32 v191, v202 offset:832
	ds_read_b32 v192, v202 offset:896
	ds_read_b32 v193, v202 offset:960
	s_waitcnt lgkmcnt(15)
	v_add_u32_e32 v172, v172, v200
	global_load_dwordx4 v[16:19], v172, s[14:15]
	s_waitcnt lgkmcnt(14)
	v_add_u32_e32 v173, v173, v200
	global_load_dwordx4 v[24:27], v173, s[14:15]
	s_waitcnt lgkmcnt(13)
	v_add_u32_e32 v174, v174, v200
	global_load_dwordx4 v[32:35], v174, s[14:15]
	s_waitcnt lgkmcnt(12)
	v_add_u32_e32 v175, v175, v200
	global_load_dwordx4 v[40:43], v175, s[14:15]
	s_waitcnt lgkmcnt(11)
	v_add_u32_e32 v176, v176, v200
	global_load_dwordx4 v[48:51], v176, s[14:15]
	s_waitcnt lgkmcnt(10)
	v_add_u32_e32 v177, v177, v200
	global_load_dwordx4 v[56:59], v177, s[14:15]
	s_waitcnt lgkmcnt(9)
	v_add_u32_e32 v178, v178, v200
	global_load_dwordx4 v[64:67], v178, s[14:15]
	s_waitcnt lgkmcnt(8)
	v_add_u32_e32 v179, v179, v200
	global_load_dwordx4 v[72:75], v179, s[14:15]
	s_waitcnt lgkmcnt(7)
	v_add_u32_e32 v180, v180, v200
	global_load_dwordx4 v[90:93], v180, s[14:15]
	s_waitcnt lgkmcnt(6)
	v_add_u32_e32 v181, v181, v200
	global_load_dwordx4 v[98:101], v181, s[14:15]
	s_waitcnt lgkmcnt(5)
	v_add_u32_e32 v188, v188, v200
	global_load_dwordx4 v[106:109], v188, s[14:15]
	s_waitcnt lgkmcnt(4)
	v_add_u32_e32 v189, v189, v200
	global_load_dwordx4 v[114:117], v189, s[14:15]
	s_waitcnt lgkmcnt(3)
	v_add_u32_e32 v190, v190, v200
	global_load_dwordx4 v[122:125], v190, s[14:15]
	s_waitcnt lgkmcnt(2)
	v_add_u32_e32 v191, v191, v200
	global_load_dwordx4 v[132:135], v191, s[14:15]
	s_waitcnt lgkmcnt(1)
	v_add_u32_e32 v192, v192, v200
	global_load_dwordx4 v[140:143], v192, s[14:15]
	s_waitcnt lgkmcnt(0)
	v_add_u32_e32 v193, v193, v200
	global_load_dwordx4 v[148:151], v193, s[14:15]
	ds_read_b32 v172, v202 offset:32
	ds_read_b32 v173, v202 offset:96
	ds_read_b32 v174, v202 offset:160
	ds_read_b32 v175, v202 offset:224
	ds_read_b32 v176, v202 offset:288
	ds_read_b32 v177, v202 offset:352
	ds_read_b32 v178, v202 offset:416
	ds_read_b32 v179, v202 offset:480
	ds_read_b32 v180, v202 offset:544
	ds_read_b32 v181, v202 offset:608
	ds_read_b32 v188, v202 offset:672
	ds_read_b32 v189, v202 offset:736
	ds_read_b32 v190, v202 offset:800
	ds_read_b32 v191, v202 offset:864
	ds_read_b32 v192, v202 offset:928
	ds_read_b32 v193, v202 offset:992
	s_waitcnt lgkmcnt(15)
	v_add_u32_e32 v172, v172, v200
	global_load_dwordx4 v[20:23], v172, s[14:15]
	s_waitcnt lgkmcnt(14)
	v_add_u32_e32 v173, v173, v200
	global_load_dwordx4 v[28:31], v173, s[14:15]
	s_waitcnt lgkmcnt(13)
	v_add_u32_e32 v174, v174, v200
	global_load_dwordx4 v[36:39], v174, s[14:15]
	s_waitcnt lgkmcnt(12)
	v_add_u32_e32 v175, v175, v200
	global_load_dwordx4 v[44:47], v175, s[14:15]
	s_waitcnt lgkmcnt(11)
	v_add_u32_e32 v176, v176, v200
	global_load_dwordx4 v[52:55], v176, s[14:15]
	s_waitcnt lgkmcnt(10)
	v_add_u32_e32 v177, v177, v200
	global_load_dwordx4 v[60:63], v177, s[14:15]
	s_waitcnt lgkmcnt(9)
	v_add_u32_e32 v178, v178, v200
	global_load_dwordx4 v[68:71], v178, s[14:15]
	s_waitcnt lgkmcnt(8)
	v_add_u32_e32 v179, v179, v200
	global_load_dwordx4 v[76:79], v179, s[14:15]
	s_waitcnt lgkmcnt(7)
	v_add_u32_e32 v180, v180, v200
	global_load_dwordx4 v[94:97], v180, s[14:15]
	s_waitcnt lgkmcnt(6)
	v_add_u32_e32 v181, v181, v200
	global_load_dwordx4 v[102:105], v181, s[14:15]
	s_waitcnt lgkmcnt(5)
	v_add_u32_e32 v188, v188, v200
	global_load_dwordx4 v[110:113], v188, s[14:15]
	s_waitcnt lgkmcnt(4)
	v_add_u32_e32 v189, v189, v200
	global_load_dwordx4 v[118:121], v189, s[14:15]
	s_waitcnt lgkmcnt(3)
	v_add_u32_e32 v190, v190, v200
	global_load_dwordx4 v[128:131], v190, s[14:15]
	s_waitcnt lgkmcnt(2)
	v_add_u32_e32 v191, v191, v200
	global_load_dwordx4 v[136:139], v191, s[14:15]
	s_waitcnt lgkmcnt(1)
	v_add_u32_e32 v192, v192, v200
	global_load_dwordx4 v[144:147], v192, s[14:15]
	s_waitcnt lgkmcnt(0)
	v_add_u32_e32 v193, v193, v200
	global_load_dwordx4 v[152:155], v193, s[14:15]
	v_lshl_add_u32 v81, v160, 5, v167
	v_readfirstlane_b32 s2, v85
	s_nop 1
	s_cmp_eq_u32 s2, 0x100
	s_cbranch_scc1 .Lqk_full
;   __device__ __forceinline__ half_t* mm() const { return (half_t*)(ws() + OFF_mm); }
; __device__ __forceinline__ void dsa_item(const KP& p, int b, int tile, char* smem) {
;     ...
;       for (int mm = 0; mm < 8; ++mm) {
;         const int m = mg * 8 + mm;
;         const int pos = m * 16 + col;
;         const int s = (pos < nsel) ? (int)sel[tk * 256 + pos] : 0;
;         const half_t* kp = ub + (size_t)s * NU + C_BK + hq * 8;
;         const h8 a0 = *(const h8*)kp, a1 = *(const h8*)(kp + 32);
;         f32x4 d = {0.f, 0.f, 0.f, 0.f};
;         d = __builtin_amdgcn_mfma_f32_16x16x32_f16(a0, q0, d, 0, 0, 0);
;         d = __builtin_amdgcn_mfma_f32_16x16x32_f16(a1, q1, d, 0, 0, 0);
; #pragma unroll
;         for (int r = 0; r < 4; ++r) {
;           const int pp = m * 16 + hq * 4 + r;
;           const float v = (pp < nsel) ? d[r] * 0.125f : NEGF;
;           mx = fmaxf(mx, v);
;           if (col < 8) pbuf[pp * 8 + col] = v;
;         }
	s_waitcnt vmcnt(15)
	ds_write_b128 v198, v[16:19]
	ds_write_b128 v198, v[20:23] offset:1152
	ds_read_b128 v[16:19], v199
	ds_read_b128 v[20:23], v199 offset:64
	s_waitcnt vmcnt(14)
	ds_write_b128 v198, v[24:27]
	ds_write_b128 v198, v[28:31] offset:1152
	ds_read_b128 v[24:27], v199
	ds_read_b128 v[28:31], v199 offset:64
	s_waitcnt lgkmcnt(4)
	v_mfma_f32_16x16x32_f16 v[10:13], v[16:19], v[6:9], 0
	v_mfma_f32_16x16x32_f16 v[10:13], v[20:23], v[2:5], v[10:13]
	s_nop 4
	s_waitcnt vmcnt(13)
	ds_write_b128 v198, v[32:35]
	ds_write_b128 v198, v[36:39] offset:1152
	ds_read_b128 v[32:35], v199
	ds_read_b128 v[36:39], v199 offset:64
	s_waitcnt lgkmcnt(4)
	v_mfma_f32_16x16x32_f16 v[194:197], v[24:27], v[6:9], 0
	v_mfma_f32_16x16x32_f16 v[194:197], v[28:31], v[2:5], v[194:197]
	v_or_b32_e32 v80, 0, v160
	v_cmp_lt_i32_e32 vcc, v80, v85
	v_cmp_lt_i32_e64 s[46:47], v80, v171
	s_nop 1
	v_cndmask_b32_e32 v10, v242, v10, vcc
	v_cndmask_b32_e64 v11, v242, v11, s[46:47]
	v_cmp_lt_i32_e32 vcc, v80, v156
	v_cmp_lt_i32_e64 s[46:47], v80, v158
	v_max3_f32 v15, v15, v10, v11
	s_nop 0
	v_cndmask_b32_e32 v12, v242, v12, vcc
	v_cndmask_b32_e64 v13, v242, v13, s[46:47]
	v_max3_f32 v15, v15, v12, v13
	s_and_saveexec_b64 s[2:3], s[38:39]
	ds_write_b32 v81, v10
	ds_write_b32 v81, v11 offset:32
	ds_write_b32 v81, v12 offset:64
	ds_write_b32 v81, v13 offset:96
	s_or_b64 exec, exec, s[2:3]
	s_waitcnt vmcnt(12)
	ds_write_b128 v198, v[40:43]
	ds_write_b128 v198, v[44:47] offset:1152
	ds_read_b128 v[40:43], v199
	ds_read_b128 v[44:47], v199 offset:64
	s_waitcnt lgkmcnt(8)
	v_mfma_f32_16x16x32_f16 v[10:13], v[32:35], v[6:9], 0
	v_mfma_f32_16x16x32_f16 v[10:13], v[36:39], v[2:5], v[10:13]
	v_or_b32_e32 v80, 16, v160
	v_cmp_lt_i32_e32 vcc, v80, v85
	v_cmp_lt_i32_e64 s[46:47], v80, v171
	s_nop 1
	v_cndmask_b32_e32 v194, v242, v194, vcc
	v_cndmask_b32_e64 v195, v242, v195, s[46:47]
	v_cmp_lt_i32_e32 vcc, v80, v156
	v_cmp_lt_i32_e64 s[46:47], v80, v158
	v_max3_f32 v15, v15, v194, v195
	s_nop 0
	v_cndmask_b32_e32 v196, v242, v196, vcc
	v_cndmask_b32_e64 v197, v242, v197, s[46:47]
	v_max3_f32 v15, v15, v196, v197
	s_and_saveexec_b64 s[2:3], s[38:39]
	ds_write_b32 v81, v194 offset:512
	ds_write_b32 v81, v195 offset:544
	ds_write_b32 v81, v196 offset:576
	ds_write_b32 v81, v197 offset:608
	s_or_b64 exec, exec, s[2:3]
	s_waitcnt vmcnt(11)
	ds_write_b128 v198, v[48:51]
	ds_write_b128 v198, v[52:55] offset:1152
	ds_read_b128 v[48:51], v199
	ds_read_b128 v[52:55], v199 offset:64
	s_waitcnt lgkmcnt(8)
	v_mfma_f32_16x16x32_f16 v[194:197], v[40:43], v[6:9], 0
	v_mfma_f32_16x16x32_f16 v[194:197], v[44:47], v[2:5], v[194:197]
	v_or_b32_e32 v80, 32, v160
	v_cmp_lt_i32_e32 vcc, v80, v85
	v_cmp_lt_i32_e64 s[46:47], v80, v171
	s_nop 1
	v_cndmask_b32_e32 v10, v242, v10, vcc
	v_cndmask_b32_e64 v11, v242, v11, s[46:47]
	v_cmp_lt_i32_e32 vcc, v80, v156
	v_cmp_lt_i32_e64 s[46:47], v80, v158
	v_max3_f32 v15, v15, v10, v11
	s_nop 0
	v_cndmask_b32_e32 v12, v242, v12, vcc
	v_cndmask_b32_e64 v13, v242, v13, s[46:47]
	v_max3_f32 v15, v15, v12, v13
	s_and_saveexec_b64 s[2:3], s[38:39]
	ds_write_b32 v81, v10 offset:1024
	ds_write_b32 v81, v11 offset:1056
	ds_write_b32 v81, v12 offset:1088
	ds_write_b32 v81, v13 offset:1120
	s_or_b64 exec, exec, s[2:3]
	s_waitcnt vmcnt(10)
	ds_write_b128 v198, v[56:59]
	ds_write_b128 v198, v[60:63] offset:1152
	ds_read_b128 v[56:59], v199
	ds_read_b128 v[60:63], v199 offset:64
	s_waitcnt lgkmcnt(8)
	v_mfma_f32_16x16x32_f16 v[10:13], v[48:51], v[6:9], 0
	v_mfma_f32_16x16x32_f16 v[10:13], v[52:55], v[2:5], v[10:13]
	v_or_b32_e32 v80, 48, v160
	v_cmp_lt_i32_e32 vcc, v80, v85
	v_cmp_lt_i32_e64 s[46:47], v80, v171
	s_nop 1
	v_cndmask_b32_e32 v194, v242, v194, vcc
	v_cndmask_b32_e64 v195, v242, v195, s[46:47]
	v_cmp_lt_i32_e32 vcc, v80, v156
	v_cmp_lt_i32_e64 s[46:47], v80, v158
	v_max3_f32 v15, v15, v194, v195
	s_nop 0
	v_cndmask_b32_e32 v196, v242, v196, vcc
	v_cndmask_b32_e64 v197, v242, v197, s[46:47]
	v_max3_f32 v15, v15, v196, v197
	s_and_saveexec_b64 s[2:3], s[38:39]
	ds_write_b32 v81, v194 offset:1536
	ds_write_b32 v81, v195 offset:1568
	ds_write_b32 v81, v196 offset:1600
	ds_write_b32 v81, v197 offset:1632
	s_or_b64 exec, exec, s[2:3]
	s_waitcnt vmcnt(9)
	ds_write_b128 v198, v[64:67]
	ds_write_b128 v198, v[68:71] offset:1152
	ds_read_b128 v[64:67], v199
	ds_read_b128 v[68:71], v199 offset:64
	s_waitcnt lgkmcnt(8)
	v_mfma_f32_16x16x32_f16 v[194:197], v[56:59], v[6:9], 0
	v_mfma_f32_16x16x32_f16 v[194:197], v[60:63], v[2:5], v[194:197]
	v_or_b32_e32 v80, 64, v160
	v_cmp_lt_i32_e32 vcc, v80, v85
	v_cmp_lt_i32_e64 s[46:47], v80, v171
	s_nop 1
	v_cndmask_b32_e32 v10, v242, v10, vcc
	v_cndmask_b32_e64 v11, v242, v11, s[46:47]
	v_cmp_lt_i32_e32 vcc, v80, v156
	v_cmp_lt_i32_e64 s[46:47], v80, v158
	v_max3_f32 v15, v15, v10, v11
	s_nop 0
	v_cndmask_b32_e32 v12, v242, v12, vcc
	v_cndmask_b32_e64 v13, v242, v13, s[46:47]
	v_max3_f32 v15, v15, v12, v13
	s_and_saveexec_b64 s[2:3], s[38:39]
	ds_write_b32 v81, v10 offset:2048
	ds_write_b32 v81, v11 offset:2080
	ds_write_b32 v81, v12 offset:2112
	ds_write_b32 v81, v13 offset:2144
	s_or_b64 exec, exec, s[2:3]
	s_waitcnt vmcnt(8)
	ds_write_b128 v198, v[72:75]
	ds_write_b128 v198, v[76:79] offset:1152
	ds_read_b128 v[72:75], v199
	ds_read_b128 v[76:79], v199 offset:64
	s_waitcnt lgkmcnt(8)
;   __device__ __forceinline__ half_t* mm() const { return (half_t*)(ws() + OFF_mm); }
; __device__ __forceinline__ void dsa_item(const KP& p, int b, int tile, char* smem) {
;     ...
;       for (int mm = 0; mm < 8; ++mm) {
;         const int m = mg * 8 + mm;
;         const int pos = m * 16 + col;
;         const int s = (pos < nsel) ? (int)sel[tk * 256 + pos] : 0;
;         const half_t* kp = ub + (size_t)s * NU + C_BK + hq * 8;
;         const h8 a0 = *(const h8*)kp, a1 = *(const h8*)(kp + 32);
;         f32x4 d = {0.f, 0.f, 0.f, 0.f};
;         d = __builtin_amdgcn_mfma_f32_16x16x32_f16(a0, q0, d, 0, 0, 0);
;         d = __builtin_amdgcn_mfma_f32_16x16x32_f16(a1, q1, d, 0, 0, 0);
; #pragma unroll
;         for (int r = 0; r < 4; ++r) {
;           const int pp = m * 16 + hq * 4 + r;
;           const float v = (pp < nsel) ? d[r] * 0.125f : NEGF;
;           mx = fmaxf(mx, v);
;           if (col < 8) pbuf[pp * 8 + col] = v;
;         }
	v_mfma_f32_16x16x32_f16 v[10:13], v[64:67], v[6:9], 0
	v_mfma_f32_16x16x32_f16 v[10:13], v[68:71], v[2:5], v[10:13]
	v_or_b32_e32 v80, 0x50, v160
	v_cmp_lt_i32_e32 vcc, v80, v85
	v_cmp_lt_i32_e64 s[46:47], v80, v171
	s_nop 1
	v_cndmask_b32_e32 v194, v242, v194, vcc
	v_cndmask_b32_e64 v195, v242, v195, s[46:47]
	v_cmp_lt_i32_e32 vcc, v80, v156
	v_cmp_lt_i32_e64 s[46:47], v80, v158
	v_max3_f32 v15, v15, v194, v195
	s_nop 0
	v_cndmask_b32_e32 v196, v242, v196, vcc
	v_cndmask_b32_e64 v197, v242, v197, s[46:47]
	v_max3_f32 v15, v15, v196, v197
	s_and_saveexec_b64 s[2:3], s[38:39]
	ds_write_b32 v81, v194 offset:2560
	ds_write_b32 v81, v195 offset:2592
	ds_write_b32 v81, v196 offset:2624
	ds_write_b32 v81, v197 offset:2656
	s_or_b64 exec, exec, s[2:3]
	s_waitcnt vmcnt(7)
	ds_write_b128 v198, v[90:93]
	ds_write_b128 v198, v[94:97] offset:1152
	ds_read_b128 v[90:93], v199
	ds_read_b128 v[94:97], v199 offset:64
	s_waitcnt lgkmcnt(8)
	v_mfma_f32_16x16x32_f16 v[194:197], v[72:75], v[6:9], 0
	v_mfma_f32_16x16x32_f16 v[194:197], v[76:79], v[2:5], v[194:197]
	v_or_b32_e32 v80, 0x60, v160
	v_cmp_lt_i32_e32 vcc, v80, v85
	v_cmp_lt_i32_e64 s[46:47], v80, v171
	s_nop 1
	v_cndmask_b32_e32 v10, v242, v10, vcc
	v_cndmask_b32_e64 v11, v242, v11, s[46:47]
	v_cmp_lt_i32_e32 vcc, v80, v156
	v_cmp_lt_i32_e64 s[46:47], v80, v158
	v_max3_f32 v15, v15, v10, v11
	s_nop 0
	v_cndmask_b32_e32 v12, v242, v12, vcc
	v_cndmask_b32_e64 v13, v242, v13, s[46:47]
	v_max3_f32 v15, v15, v12, v13
	s_and_saveexec_b64 s[2:3], s[38:39]
	ds_write_b32 v81, v10 offset:3072
	ds_write_b32 v81, v11 offset:3104
	ds_write_b32 v81, v12 offset:3136
	ds_write_b32 v81, v13 offset:3168
	s_or_b64 exec, exec, s[2:3]
	s_waitcnt vmcnt(6)
	ds_write_b128 v198, v[98:101]
	ds_write_b128 v198, v[102:105] offset:1152
	ds_read_b128 v[98:101], v199
	ds_read_b128 v[102:105], v199 offset:64
	s_waitcnt lgkmcnt(8)
	v_mfma_f32_16x16x32_f16 v[10:13], v[90:93], v[6:9], 0
	v_mfma_f32_16x16x32_f16 v[10:13], v[94:97], v[2:5], v[10:13]
	v_or_b32_e32 v80, 0x70, v160
	v_cmp_lt_i32_e32 vcc, v80, v85
	v_cmp_lt_i32_e64 s[46:47], v80, v171
	s_nop 1
	v_cndmask_b32_e32 v194, v242, v194, vcc
	v_cndmask_b32_e64 v195, v242, v195, s[46:47]
	v_cmp_lt_i32_e32 vcc, v80, v156
	v_cmp_lt_i32_e64 s[46:47], v80, v158
	v_max3_f32 v15, v15, v194, v195
	s_nop 0
	v_cndmask_b32_e32 v196, v242, v196, vcc
	v_cndmask_b32_e64 v197, v242, v197, s[46:47]
	v_max3_f32 v15, v15, v196, v197
	s_and_saveexec_b64 s[2:3], s[38:39]
	ds_write_b32 v81, v194 offset:3584
	ds_write_b32 v81, v195 offset:3616
	ds_write_b32 v81, v196 offset:3648
	ds_write_b32 v81, v197 offset:3680
	s_or_b64 exec, exec, s[2:3]
	s_waitcnt vmcnt(5)
	ds_write_b128 v198, v[106:109]
	ds_write_b128 v198, v[110:113] offset:1152
	ds_read_b128 v[106:109], v199
	ds_read_b128 v[110:113], v199 offset:64
	s_waitcnt lgkmcnt(8)
	v_mfma_f32_16x16x32_f16 v[194:197], v[98:101], v[6:9], 0
	v_mfma_f32_16x16x32_f16 v[194:197], v[102:105], v[2:5], v[194:197]
	v_or_b32_e32 v80, 0x80, v160
	v_cmp_lt_i32_e32 vcc, v80, v85
	v_cmp_lt_i32_e64 s[46:47], v80, v171
	s_nop 1
	v_cndmask_b32_e32 v10, v242, v10, vcc
	v_cndmask_b32_e64 v11, v242, v11, s[46:47]
	v_cmp_lt_i32_e32 vcc, v80, v156
	v_cmp_lt_i32_e64 s[46:47], v80, v158
	v_max3_f32 v15, v15, v10, v11
	s_nop 0
	v_cndmask_b32_e32 v12, v242, v12, vcc
	v_cndmask_b32_e64 v13, v242, v13, s[46:47]
	v_max3_f32 v15, v15, v12, v13
	s_and_saveexec_b64 s[2:3], s[38:39]
	ds_write_b32 v81, v10 offset:4096
	ds_write_b32 v81, v11 offset:4128
	ds_write_b32 v81, v12 offset:4160
	ds_write_b32 v81, v13 offset:4192
	s_or_b64 exec, exec, s[2:3]
	s_waitcnt vmcnt(4)
	ds_write_b128 v198, v[114:117]
	ds_write_b128 v198, v[118:121] offset:1152
	ds_read_b128 v[114:117], v199
	ds_read_b128 v[118:121], v199 offset:64
	s_waitcnt lgkmcnt(8)
	v_mfma_f32_16x16x32_f16 v[10:13], v[106:109], v[6:9], 0
	v_mfma_f32_16x16x32_f16 v[10:13], v[110:113], v[2:5], v[10:13]
	v_or_b32_e32 v80, 0x90, v160
	v_cmp_lt_i32_e32 vcc, v80, v85
	v_cmp_lt_i32_e64 s[46:47], v80, v171
	s_nop 1
	v_cndmask_b32_e32 v194, v242, v194, vcc
	v_cndmask_b32_e64 v195, v242, v195, s[46:47]
	v_cmp_lt_i32_e32 vcc, v80, v156
	v_cmp_lt_i32_e64 s[46:47], v80, v158
	v_max3_f32 v15, v15, v194, v195
	s_nop 0
	v_cndmask_b32_e32 v196, v242, v196, vcc
	v_cndmask_b32_e64 v197, v242, v197, s[46:47]
	v_max3_f32 v15, v15, v196, v197
	s_and_saveexec_b64 s[2:3], s[38:39]
	ds_write_b32 v81, v194 offset:4608
	ds_write_b32 v81, v195 offset:4640
	ds_write_b32 v81, v196 offset:4672
	ds_write_b32 v81, v197 offset:4704
	s_or_b64 exec, exec, s[2:3]
	s_waitcnt vmcnt(3)
	ds_write_b128 v198, v[122:125]
	ds_write_b128 v198, v[128:131] offset:1152
	ds_read_b128 v[122:125], v199
	ds_read_b128 v[128:131], v199 offset:64
	s_waitcnt lgkmcnt(8)
	v_mfma_f32_16x16x32_f16 v[194:197], v[114:117], v[6:9], 0
	v_mfma_f32_16x16x32_f16 v[194:197], v[118:121], v[2:5], v[194:197]
	v_or_b32_e32 v80, 0xa0, v160
	v_cmp_lt_i32_e32 vcc, v80, v85
	v_cmp_lt_i32_e64 s[46:47], v80, v171
	s_nop 1
	v_cndmask_b32_e32 v10, v242, v10, vcc
	v_cndmask_b32_e64 v11, v242, v11, s[46:47]
	v_cmp_lt_i32_e32 vcc, v80, v156
	v_cmp_lt_i32_e64 s[46:47], v80, v158
	v_max3_f32 v15, v15, v10, v11
	s_nop 0
	v_cndmask_b32_e32 v12, v242, v12, vcc
	v_cndmask_b32_e64 v13, v242, v13, s[46:47]
	v_max3_f32 v15, v15, v12, v13
	s_and_saveexec_b64 s[2:3], s[38:39]
	ds_write_b32 v81, v10 offset:5120
	ds_write_b32 v81, v11 offset:5152
	ds_write_b32 v81, v12 offset:5184
	ds_write_b32 v81, v13 offset:5216
	s_or_b64 exec, exec, s[2:3]
	s_waitcnt vmcnt(2)
	ds_write_b128 v198, v[132:135]
	ds_write_b128 v198, v[136:139] offset:1152
	ds_read_b128 v[132:135], v199
	ds_read_b128 v[136:139], v199 offset:64
	s_waitcnt lgkmcnt(8)
;   __device__ __forceinline__ half_t* mm() const { return (half_t*)(ws() + OFF_mm); }
; __device__ __forceinline__ void dsa_item(const KP& p, int b, int tile, char* smem) {
;     ...
;       for (int mm = 0; mm < 8; ++mm) {
;         const int m = mg * 8 + mm;
;         const int pos = m * 16 + col;
;         const int s = (pos < nsel) ? (int)sel[tk * 256 + pos] : 0;
;         const half_t* kp = ub + (size_t)s * NU + C_BK + hq * 8;
;         const h8 a0 = *(const h8*)kp, a1 = *(const h8*)(kp + 32);
;         f32x4 d = {0.f, 0.f, 0.f, 0.f};
;         d = __builtin_amdgcn_mfma_f32_16x16x32_f16(a0, q0, d, 0, 0, 0);
;         d = __builtin_amdgcn_mfma_f32_16x16x32_f16(a1, q1, d, 0, 0, 0);
; #pragma unroll
;         for (int r = 0; r < 4; ++r) {
;           const int pp = m * 16 + hq * 4 + r;
;           const float v = (pp < nsel) ? d[r] * 0.125f : NEGF;
;           mx = fmaxf(mx, v);
;           if (col < 8) pbuf[pp * 8 + col] = v;
;         }
	v_mfma_f32_16x16x32_f16 v[10:13], v[122:125], v[6:9], 0
	v_mfma_f32_16x16x32_f16 v[10:13], v[128:131], v[2:5], v[10:13]
	v_or_b32_e32 v80, 0xb0, v160
	v_cmp_lt_i32_e32 vcc, v80, v85
	v_cmp_lt_i32_e64 s[46:47], v80, v171
	s_nop 1
	v_cndmask_b32_e32 v194, v242, v194, vcc
	v_cndmask_b32_e64 v195, v242, v195, s[46:47]
	v_cmp_lt_i32_e32 vcc, v80, v156
	v_cmp_lt_i32_e64 s[46:47], v80, v158
	v_max3_f32 v15, v15, v194, v195
	s_nop 0
	v_cndmask_b32_e32 v196, v242, v196, vcc
	v_cndmask_b32_e64 v197, v242, v197, s[46:47]
	v_max3_f32 v15, v15, v196, v197
	s_and_saveexec_b64 s[2:3], s[38:39]
	ds_write_b32 v81, v194 offset:5632
	ds_write_b32 v81, v195 offset:5664
	ds_write_b32 v81, v196 offset:5696
	ds_write_b32 v81, v197 offset:5728
	s_or_b64 exec, exec, s[2:3]
	s_waitcnt vmcnt(1)
	ds_write_b128 v198, v[140:143]
	ds_write_b128 v198, v[144:147] offset:1152
	ds_read_b128 v[140:143], v199
	ds_read_b128 v[144:147], v199 offset:64
	s_waitcnt lgkmcnt(8)
	v_mfma_f32_16x16x32_f16 v[194:197], v[132:135], v[6:9], 0
	v_mfma_f32_16x16x32_f16 v[194:197], v[136:139], v[2:5], v[194:197]
	v_or_b32_e32 v80, 0xc0, v160
	v_cmp_lt_i32_e32 vcc, v80, v85
	v_cmp_lt_i32_e64 s[46:47], v80, v171
	s_nop 1
	v_cndmask_b32_e32 v10, v242, v10, vcc
	v_cndmask_b32_e64 v11, v242, v11, s[46:47]
	v_cmp_lt_i32_e32 vcc, v80, v156
	v_cmp_lt_i32_e64 s[46:47], v80, v158
	v_max3_f32 v15, v15, v10, v11
	s_nop 0
	v_cndmask_b32_e32 v12, v242, v12, vcc
	v_cndmask_b32_e64 v13, v242, v13, s[46:47]
	v_max3_f32 v15, v15, v12, v13
	s_and_saveexec_b64 s[2:3], s[38:39]
	ds_write_b32 v81, v10 offset:6144
	ds_write_b32 v81, v11 offset:6176
	ds_write_b32 v81, v12 offset:6208
	ds_write_b32 v81, v13 offset:6240
	s_or_b64 exec, exec, s[2:3]
	s_waitcnt vmcnt(0)
	ds_write_b128 v198, v[148:151]
	ds_write_b128 v198, v[152:155] offset:1152
	ds_read_b128 v[148:151], v199
	ds_read_b128 v[152:155], v199 offset:64
	s_waitcnt lgkmcnt(8)
	v_mfma_f32_16x16x32_f16 v[10:13], v[140:143], v[6:9], 0
	v_mfma_f32_16x16x32_f16 v[10:13], v[144:147], v[2:5], v[10:13]
	v_or_b32_e32 v80, 0xd0, v160
	v_cmp_lt_i32_e32 vcc, v80, v85
	v_cmp_lt_i32_e64 s[46:47], v80, v171
	s_nop 1
	v_cndmask_b32_e32 v194, v242, v194, vcc
	v_cndmask_b32_e64 v195, v242, v195, s[46:47]
	v_cmp_lt_i32_e32 vcc, v80, v156
	v_cmp_lt_i32_e64 s[46:47], v80, v158
	v_max3_f32 v15, v15, v194, v195
	s_nop 0
	v_cndmask_b32_e32 v196, v242, v196, vcc
	v_cndmask_b32_e64 v197, v242, v197, s[46:47]
	v_max3_f32 v15, v15, v196, v197
	s_and_saveexec_b64 s[2:3], s[38:39]
	ds_write_b32 v81, v194 offset:6656
	ds_write_b32 v81, v195 offset:6688
	ds_write_b32 v81, v196 offset:6720
	ds_write_b32 v81, v197 offset:6752
	s_or_b64 exec, exec, s[2:3]
	s_waitcnt lgkmcnt(4)
	v_mfma_f32_16x16x32_f16 v[194:197], v[148:151], v[6:9], 0
	v_mfma_f32_16x16x32_f16 v[194:197], v[152:155], v[2:5], v[194:197]
	v_or_b32_e32 v80, 0xe0, v160
	v_cmp_lt_i32_e32 vcc, v80, v85
	v_cmp_lt_i32_e64 s[46:47], v80, v171
	s_nop 1
	v_cndmask_b32_e32 v10, v242, v10, vcc
	v_cndmask_b32_e64 v11, v242, v11, s[46:47]
	v_cmp_lt_i32_e32 vcc, v80, v156
	v_cmp_lt_i32_e64 s[46:47], v80, v158
	v_max3_f32 v15, v15, v10, v11
	s_nop 0
	v_cndmask_b32_e32 v12, v242, v12, vcc
	v_cndmask_b32_e64 v13, v242, v13, s[46:47]
	v_max3_f32 v15, v15, v12, v13
	s_and_saveexec_b64 s[2:3], s[38:39]
	ds_write_b32 v81, v10 offset:7168
	ds_write_b32 v81, v11 offset:7200
	ds_write_b32 v81, v12 offset:7232
	ds_write_b32 v81, v13 offset:7264
	s_or_b64 exec, exec, s[2:3]
	s_nop 7
	v_or_b32_e32 v80, 0xf0, v160
	v_cmp_lt_i32_e32 vcc, v80, v85
	v_cmp_lt_i32_e64 s[46:47], v80, v171
	s_nop 1
	v_cndmask_b32_e32 v194, v242, v194, vcc
	v_cndmask_b32_e64 v195, v242, v195, s[46:47]
	v_cmp_lt_i32_e32 vcc, v80, v156
	v_cmp_lt_i32_e64 s[46:47], v80, v158
	v_max3_f32 v15, v15, v194, v195
	s_nop 0
	v_cndmask_b32_e32 v196, v242, v196, vcc
	v_cndmask_b32_e64 v197, v242, v197, s[46:47]
	v_max3_f32 v15, v15, v196, v197
	s_and_saveexec_b64 s[2:3], s[38:39]
	ds_write_b32 v81, v194 offset:7680
	ds_write_b32 v81, v195 offset:7712
	ds_write_b32 v81, v196 offset:7744
	ds_write_b32 v81, v197 offset:7776
	s_or_b64 exec, exec, s[2:3]
	s_branch .LBB0_1509
.Lqk_full:
	s_waitcnt vmcnt(15)
	ds_write_b128 v198, v[16:19]
	ds_write_b128 v198, v[20:23] offset:1152
	ds_read_b128 v[16:19], v199
	ds_read_b128 v[20:23], v199 offset:64
	s_waitcnt vmcnt(14)
	ds_write_b128 v198, v[24:27]
	ds_write_b128 v198, v[28:31] offset:1152
	ds_read_b128 v[24:27], v199
	ds_read_b128 v[28:31], v199 offset:64
	s_waitcnt lgkmcnt(4)
	v_mfma_f32_16x16x32_f16 v[10:13], v[16:19], v[6:9], 0
	v_mfma_f32_16x16x32_f16 v[10:13], v[20:23], v[2:5], v[10:13]
	s_nop 4
	s_waitcnt vmcnt(13)
	ds_write_b128 v198, v[32:35]
	ds_write_b128 v198, v[36:39] offset:1152
	ds_read_b128 v[32:35], v199
	ds_read_b128 v[36:39], v199 offset:64
	s_waitcnt lgkmcnt(4)
	v_mfma_f32_16x16x32_f16 v[194:197], v[24:27], v[6:9], 0
	v_mfma_f32_16x16x32_f16 v[194:197], v[28:31], v[2:5], v[194:197]
	v_max3_f32 v15, v15, v10, v11
	v_max3_f32 v15, v15, v12, v13
	s_and_saveexec_b64 s[2:3], s[38:39]
	ds_write_b32 v81, v10
	ds_write_b32 v81, v11 offset:32
	ds_write_b32 v81, v12 offset:64
	ds_write_b32 v81, v13 offset:96
	s_or_b64 exec, exec, s[2:3]
	s_waitcnt vmcnt(12)
	ds_write_b128 v198, v[40:43]
	ds_write_b128 v198, v[44:47] offset:1152
	ds_read_b128 v[40:43], v199
	ds_read_b128 v[44:47], v199 offset:64
	s_waitcnt lgkmcnt(8)
	v_mfma_f32_16x16x32_f16 v[10:13], v[32:35], v[6:9], 0
	v_mfma_f32_16x16x32_f16 v[10:13], v[36:39], v[2:5], v[10:13]
	v_max3_f32 v15, v15, v194, v195
	v_max3_f32 v15, v15, v196, v197
	s_and_saveexec_b64 s[2:3], s[38:39]
	ds_write_b32 v81, v194 offset:512
	ds_write_b32 v81, v195 offset:544
	ds_write_b32 v81, v196 offset:576
	ds_write_b32 v81, v197 offset:608
	s_or_b64 exec, exec, s[2:3]
	s_waitcnt vmcnt(11)
;   __device__ __forceinline__ half_t* mm() const { return (half_t*)(ws() + OFF_mm); }
; __device__ __forceinline__ void dsa_item(const KP& p, int b, int tile, char* smem) {
;     ...
;       for (int mm = 0; mm < 8; ++mm) {
;         const int m = mg * 8 + mm;
;         const int pos = m * 16 + col;
;         const int s = (pos < nsel) ? (int)sel[tk * 256 + pos] : 0;
;         const half_t* kp = ub + (size_t)s * NU + C_BK + hq * 8;
;         const h8 a0 = *(const h8*)kp, a1 = *(const h8*)(kp + 32);
;         f32x4 d = {0.f, 0.f, 0.f, 0.f};
;         d = __builtin_amdgcn_mfma_f32_16x16x32_f16(a0, q0, d, 0, 0, 0);
;         d = __builtin_amdgcn_mfma_f32_16x16x32_f16(a1, q1, d, 0, 0, 0);
; #pragma unroll
;         for (int r = 0; r < 4; ++r) {
;           const int pp = m * 16 + hq * 4 + r;
;           const float v = (pp < nsel) ? d[r] * 0.125f : NEGF;
;           mx = fmaxf(mx, v);
;           if (col < 8) pbuf[pp * 8 + col] = v;
;         }
	ds_write_b128 v198, v[48:51]
	ds_write_b128 v198, v[52:55] offset:1152
	ds_read_b128 v[48:51], v199
	ds_read_b128 v[52:55], v199 offset:64
	s_waitcnt lgkmcnt(8)
	v_mfma_f32_16x16x32_f16 v[194:197], v[40:43], v[6:9], 0
	v_mfma_f32_16x16x32_f16 v[194:197], v[44:47], v[2:5], v[194:197]
	v_max3_f32 v15, v15, v10, v11
	v_max3_f32 v15, v15, v12, v13
	s_and_saveexec_b64 s[2:3], s[38:39]
	ds_write_b32 v81, v10 offset:1024
	ds_write_b32 v81, v11 offset:1056
	ds_write_b32 v81, v12 offset:1088
	ds_write_b32 v81, v13 offset:1120
	s_or_b64 exec, exec, s[2:3]
	s_waitcnt vmcnt(10)
	ds_write_b128 v198, v[56:59]
	ds_write_b128 v198, v[60:63] offset:1152
	ds_read_b128 v[56:59], v199
	ds_read_b128 v[60:63], v199 offset:64
	s_waitcnt lgkmcnt(8)
	v_mfma_f32_16x16x32_f16 v[10:13], v[48:51], v[6:9], 0
	v_mfma_f32_16x16x32_f16 v[10:13], v[52:55], v[2:5], v[10:13]
	v_max3_f32 v15, v15, v194, v195
	v_max3_f32 v15, v15, v196, v197
	s_and_saveexec_b64 s[2:3], s[38:39]
	ds_write_b32 v81, v194 offset:1536
	ds_write_b32 v81, v195 offset:1568
	ds_write_b32 v81, v196 offset:1600
	ds_write_b32 v81, v197 offset:1632
	s_or_b64 exec, exec, s[2:3]
	s_waitcnt vmcnt(9)
	ds_write_b128 v198, v[64:67]
	ds_write_b128 v198, v[68:71] offset:1152
	ds_read_b128 v[64:67], v199
	ds_read_b128 v[68:71], v199 offset:64
	s_waitcnt lgkmcnt(8)
	v_mfma_f32_16x16x32_f16 v[194:197], v[56:59], v[6:9], 0
	v_mfma_f32_16x16x32_f16 v[194:197], v[60:63], v[2:5], v[194:197]
	v_max3_f32 v15, v15, v10, v11
	v_max3_f32 v15, v15, v12, v13
	s_and_saveexec_b64 s[2:3], s[38:39]
	ds_write_b32 v81, v10 offset:2048
	ds_write_b32 v81, v11 offset:2080
	ds_write_b32 v81, v12 offset:2112
	ds_write_b32 v81, v13 offset:2144
	s_or_b64 exec, exec, s[2:3]
	s_waitcnt vmcnt(8)
	ds_write_b128 v198, v[72:75]
	ds_write_b128 v198, v[76:79] offset:1152
	ds_read_b128 v[72:75], v199
	ds_read_b128 v[76:79], v199 offset:64
	s_waitcnt lgkmcnt(8)
	v_mfma_f32_16x16x32_f16 v[10:13], v[64:67], v[6:9], 0
	v_mfma_f32_16x16x32_f16 v[10:13], v[68:71], v[2:5], v[10:13]
	v_max3_f32 v15, v15, v194, v195
	v_max3_f32 v15, v15, v196, v197
	s_and_saveexec_b64 s[2:3], s[38:39]
	ds_write_b32 v81, v194 offset:2560
	ds_write_b32 v81, v195 offset:2592
	ds_write_b32 v81, v196 offset:2624
	ds_write_b32 v81, v197 offset:2656
	s_or_b64 exec, exec, s[2:3]
	s_waitcnt vmcnt(7)
	ds_write_b128 v198, v[90:93]
	ds_write_b128 v198, v[94:97] offset:1152
	ds_read_b128 v[90:93], v199
	ds_read_b128 v[94:97], v199 offset:64
	s_waitcnt lgkmcnt(8)
	v_mfma_f32_16x16x32_f16 v[194:197], v[72:75], v[6:9], 0
	v_mfma_f32_16x16x32_f16 v[194:197], v[76:79], v[2:5], v[194:197]
	v_max3_f32 v15, v15, v10, v11
	v_max3_f32 v15, v15, v12, v13
	s_and_saveexec_b64 s[2:3], s[38:39]
	ds_write_b32 v81, v10 offset:3072
	ds_write_b32 v81, v11 offset:3104
	ds_write_b32 v81, v12 offset:3136
	ds_write_b32 v81, v13 offset:3168
	s_or_b64 exec, exec, s[2:3]
	s_waitcnt vmcnt(6)
	ds_write_b128 v198, v[98:101]
	ds_write_b128 v198, v[102:105] offset:1152
	ds_read_b128 v[98:101], v199
	ds_read_b128 v[102:105], v199 offset:64
	s_waitcnt lgkmcnt(8)
	v_mfma_f32_16x16x32_f16 v[10:13], v[90:93], v[6:9], 0
	v_mfma_f32_16x16x32_f16 v[10:13], v[94:97], v[2:5], v[10:13]
	v_max3_f32 v15, v15, v194, v195
	v_max3_f32 v15, v15, v196, v197
	s_and_saveexec_b64 s[2:3], s[38:39]
	ds_write_b32 v81, v194 offset:3584
	ds_write_b32 v81, v195 offset:3616
	ds_write_b32 v81, v196 offset:3648
	ds_write_b32 v81, v197 offset:3680
	s_or_b64 exec, exec, s[2:3]
	s_waitcnt vmcnt(5)
	ds_write_b128 v198, v[106:109]
	ds_write_b128 v198, v[110:113] offset:1152
	ds_read_b128 v[106:109], v199
	ds_read_b128 v[110:113], v199 offset:64
	s_waitcnt lgkmcnt(8)
;   __device__ __forceinline__ half_t* mm() const { return (half_t*)(ws() + OFF_mm); }
; __device__ __forceinline__ void dsa_item(const KP& p, int b, int tile, char* smem) {
;     ...
;       for (int mm = 0; mm < 8; ++mm) {
;         const int m = mg * 8 + mm;
;         const int pos = m * 16 + col;
;         const int s = (pos < nsel) ? (int)sel[tk * 256 + pos] : 0;
;         const half_t* kp = ub + (size_t)s * NU + C_BK + hq * 8;
;         const h8 a0 = *(const h8*)kp, a1 = *(const h8*)(kp + 32);
;         f32x4 d = {0.f, 0.f, 0.f, 0.f};
;         d = __builtin_amdgcn_mfma_f32_16x16x32_f16(a0, q0, d, 0, 0, 0);
;         d = __builtin_amdgcn_mfma_f32_16x16x32_f16(a1, q1, d, 0, 0, 0);
; #pragma unroll
;         for (int r = 0; r < 4; ++r) {
;           const int pp = m * 16 + hq * 4 + r;
;           const float v = (pp < nsel) ? d[r] * 0.125f : NEGF;
;           mx = fmaxf(mx, v);
;           if (col < 8) pbuf[pp * 8 + col] = v;
;         }
	v_mfma_f32_16x16x32_f16 v[194:197], v[98:101], v[6:9], 0
	v_mfma_f32_16x16x32_f16 v[194:197], v[102:105], v[2:5], v[194:197]
	v_max3_f32 v15, v15, v10, v11
	v_max3_f32 v15, v15, v12, v13
	s_and_saveexec_b64 s[2:3], s[38:39]
	ds_write_b32 v81, v10 offset:4096
	ds_write_b32 v81, v11 offset:4128
	ds_write_b32 v81, v12 offset:4160
	ds_write_b32 v81, v13 offset:4192
	s_or_b64 exec, exec, s[2:3]
	s_waitcnt vmcnt(4)
	ds_write_b128 v198, v[114:117]
	ds_write_b128 v198, v[118:121] offset:1152
	ds_read_b128 v[114:117], v199
	ds_read_b128 v[118:121], v199 offset:64
	s_waitcnt lgkmcnt(8)
	v_mfma_f32_16x16x32_f16 v[10:13], v[106:109], v[6:9], 0
	v_mfma_f32_16x16x32_f16 v[10:13], v[110:113], v[2:5], v[10:13]
	v_max3_f32 v15, v15, v194, v195
	v_max3_f32 v15, v15, v196, v197
	s_and_saveexec_b64 s[2:3], s[38:39]
	ds_write_b32 v81, v194 offset:4608
	ds_write_b32 v81, v195 offset:4640
	ds_write_b32 v81, v196 offset:4672
	ds_write_b32 v81, v197 offset:4704
	s_or_b64 exec, exec, s[2:3]
	s_waitcnt vmcnt(3)
	ds_write_b128 v198, v[122:125]
	ds_write_b128 v198, v[128:131] offset:1152
	ds_read_b128 v[122:125], v199
	ds_read_b128 v[128:131], v199 offset:64
	s_waitcnt lgkmcnt(8)
	v_mfma_f32_16x16x32_f16 v[194:197], v[114:117], v[6:9], 0
	v_mfma_f32_16x16x32_f16 v[194:197], v[118:121], v[2:5], v[194:197]
	v_max3_f32 v15, v15, v10, v11
	v_max3_f32 v15, v15, v12, v13
	s_and_saveexec_b64 s[2:3], s[38:39]
	ds_write_b32 v81, v10 offset:5120
	ds_write_b32 v81, v11 offset:5152
	ds_write_b32 v81, v12 offset:5184
	ds_write_b32 v81, v13 offset:5216
	s_or_b64 exec, exec, s[2:3]
	s_waitcnt vmcnt(2)
	ds_write_b128 v198, v[132:135]
	ds_write_b128 v198, v[136:139] offset:1152
	ds_read_b128 v[132:135], v199
	ds_read_b128 v[136:139], v199 offset:64
	s_waitcnt lgkmcnt(8)
	v_mfma_f32_16x16x32_f16 v[10:13], v[122:125], v[6:9], 0
	v_mfma_f32_16x16x32_f16 v[10:13], v[128:131], v[2:5], v[10:13]
	v_max3_f32 v15, v15, v194, v195
	v_max3_f32 v15, v15, v196, v197
	s_and_saveexec_b64 s[2:3], s[38:39]
	ds_write_b32 v81, v194 offset:5632
	ds_write_b32 v81, v195 offset:5664
	ds_write_b32 v81, v196 offset:5696
	ds_write_b32 v81, v197 offset:5728
	s_or_b64 exec, exec, s[2:3]
	s_waitcnt vmcnt(1)
	ds_write_b128 v198, v[140:143]
	ds_write_b128 v198, v[144:147] offset:1152
	ds_read_b128 v[140:143], v199
	ds_read_b128 v[144:147], v199 offset:64
	s_waitcnt lgkmcnt(8)
	v_mfma_f32_16x16x32_f16 v[194:197], v[132:135], v[6:9], 0
	v_mfma_f32_16x16x32_f16 v[194:197], v[136:139], v[2:5], v[194:197]
	v_max3_f32 v15, v15, v10, v11
	v_max3_f32 v15, v15, v12, v13
	s_and_saveexec_b64 s[2:3], s[38:39]
	ds_write_b32 v81, v10 offset:6144
	ds_write_b32 v81, v11 offset:6176
	ds_write_b32 v81, v12 offset:6208
	ds_write_b32 v81, v13 offset:6240
	s_or_b64 exec, exec, s[2:3]
	s_waitcnt vmcnt(0)
	ds_write_b128 v198, v[148:151]
	ds_write_b128 v198, v[152:155] offset:1152
	ds_read_b128 v[148:151], v199
	ds_read_b128 v[152:155], v199 offset:64
	s_waitcnt lgkmcnt(8)
	v_mfma_f32_16x16x32_f16 v[10:13], v[140:143], v[6:9], 0
	v_mfma_f32_16x16x32_f16 v[10:13], v[144:147], v[2:5], v[10:13]
	v_max3_f32 v15, v15, v194, v195
	v_max3_f32 v15, v15, v196, v197
	s_and_saveexec_b64 s[2:3], s[38:39]
	ds_write_b32 v81, v194 offset:6656
	ds_write_b32 v81, v195 offset:6688
	ds_write_b32 v81, v196 offset:6720
	ds_write_b32 v81, v197 offset:6752
	s_or_b64 exec, exec, s[2:3]
	s_waitcnt lgkmcnt(4)
	v_mfma_f32_16x16x32_f16 v[194:197], v[148:151], v[6:9], 0
	v_mfma_f32_16x16x32_f16 v[194:197], v[152:155], v[2:5], v[194:197]
	v_max3_f32 v15, v15, v10, v11
	v_max3_f32 v15, v15, v12, v13
	s_and_saveexec_b64 s[2:3], s[38:39]
	ds_write_b32 v81, v10 offset:7168
	ds_write_b32 v81, v11 offset:7200
	ds_write_b32 v81, v12 offset:7232
	ds_write_b32 v81, v13 offset:7264
	s_or_b64 exec, exec, s[2:3]
	s_nop 7
	v_max3_f32 v15, v15, v194, v195
	v_max3_f32 v15, v15, v196, v197
	s_and_saveexec_b64 s[2:3], s[38:39]
	ds_write_b32 v81, v194 offset:7680
	ds_write_b32 v81, v195 offset:7712
	ds_write_b32 v81, v196 offset:7744
	ds_write_b32 v81, v197 offset:7776
	s_or_b64 exec, exec, s[2:3]

; __device__ __forceinline__ void dsa_item(const KP& p, int b, int tile, char* smem) {
;     ...
;     float sum = 0.f;
; #pragma unroll 4
;     for (int k = 0; k < 32; ++k) {
;       const int i = lane + 64 * k;
;       const float v = pbuf[i];
;       const float e = (v > -1e29f) ? __expf(v - mxh) : 0.f;
;       pbuf[i] = e;
;       sum += e;
;     }
.LBB0_1510:
	ds_read2st64_b32 v[16:17], v168 offset1:1
	ds_read2st64_b32 v[18:19], v168 offset0:2 offset1:3
	ds_read2st64_b32 v[20:21], v168 offset0:4 offset1:5
	ds_read2st64_b32 v[22:23], v168 offset0:6 offset1:7
	ds_read2st64_b32 v[24:25], v168 offset0:8 offset1:9
	ds_read2st64_b32 v[26:27], v168 offset0:10 offset1:11
	ds_read2st64_b32 v[28:29], v168 offset0:12 offset1:13
	ds_read2st64_b32 v[30:31], v168 offset0:14 offset1:15
	ds_read2st64_b32 v[32:33], v168 offset0:16 offset1:17
	ds_read2st64_b32 v[34:35], v168 offset0:18 offset1:19
	ds_read2st64_b32 v[36:37], v168 offset0:20 offset1:21
	ds_read2st64_b32 v[38:39], v168 offset0:22 offset1:23
	ds_read2st64_b32 v[40:41], v168 offset0:24 offset1:25
	ds_read2st64_b32 v[42:43], v168 offset0:26 offset1:27
	ds_read2st64_b32 v[44:45], v168 offset0:28 offset1:29
	ds_read2st64_b32 v[46:47], v168 offset0:30 offset1:31
	v_readfirstlane_b32 s2, v85
	s_nop 1
	s_cmp_eq_u32 s2, 0x100
	s_cbranch_scc1 .Lsm_full
	s_waitcnt lgkmcnt(14)
	v_cmp_lt_f32_e32 vcc, s75, v16
	v_cmp_lt_f32_e64 s[2:3], s75, v17
	v_cmp_lt_f32_e64 s[14:15], s75, v18
	v_cmp_lt_f32_e64 s[46:47], s75, v19
	v_sub_f32_e32 v16, v16, v2
	v_sub_f32_e32 v17, v17, v2
	v_sub_f32_e32 v18, v18, v2
	v_sub_f32_e32 v19, v19, v2
	v_mul_f32_e32 v16, 0x3e38aa3b, v16
	v_mul_f32_e32 v17, 0x3e38aa3b, v17
	v_mul_f32_e32 v18, 0x3e38aa3b, v18
	v_mul_f32_e32 v19, 0x3e38aa3b, v19
	v_exp_f32_e32 v16, v16
	v_exp_f32_e32 v17, v17
	v_exp_f32_e32 v18, v18
	v_exp_f32_e32 v19, v19
	v_cndmask_b32_e32 v16, 0, v16, vcc
	v_cndmask_b32_e64 v17, 0, v17, s[2:3]
	v_cndmask_b32_e64 v18, 0, v18, s[14:15]
	v_cndmask_b32_e64 v19, 0, v19, s[46:47]
	v_add_f32_e32 v3, v3, v16
	v_add_f32_e32 v3, v3, v17
	v_add_f32_e32 v3, v3, v18
	v_add_f32_e32 v3, v3, v19
	s_waitcnt lgkmcnt(12)
	v_cmp_lt_f32_e32 vcc, s75, v20
	v_cmp_lt_f32_e64 s[2:3], s75, v21
	v_cmp_lt_f32_e64 s[14:15], s75, v22
	v_cmp_lt_f32_e64 s[46:47], s75, v23
	v_sub_f32_e32 v20, v20, v2
	v_sub_f32_e32 v21, v21, v2
	v_sub_f32_e32 v22, v22, v2
	v_sub_f32_e32 v23, v23, v2
	v_mul_f32_e32 v20, 0x3e38aa3b, v20
	v_mul_f32_e32 v21, 0x3e38aa3b, v21
	v_mul_f32_e32 v22, 0x3e38aa3b, v22
	v_mul_f32_e32 v23, 0x3e38aa3b, v23
	v_exp_f32_e32 v20, v20
	v_exp_f32_e32 v21, v21
	v_exp_f32_e32 v22, v22
	v_exp_f32_e32 v23, v23
	v_cndmask_b32_e32 v20, 0, v20, vcc
	v_cndmask_b32_e64 v21, 0, v21, s[2:3]
	v_cndmask_b32_e64 v22, 0, v22, s[14:15]
	v_cndmask_b32_e64 v23, 0, v23, s[46:47]
	v_add_f32_e32 v3, v3, v20
	v_add_f32_e32 v3, v3, v21
	v_add_f32_e32 v3, v3, v22
	v_add_f32_e32 v3, v3, v23
	s_waitcnt lgkmcnt(10)
	v_cmp_lt_f32_e32 vcc, s75, v24
	v_cmp_lt_f32_e64 s[2:3], s75, v25
	v_cmp_lt_f32_e64 s[14:15], s75, v26
	v_cmp_lt_f32_e64 s[46:47], s75, v27
	v_sub_f32_e32 v24, v24, v2
	v_sub_f32_e32 v25, v25, v2
	v_sub_f32_e32 v26, v26, v2
	v_sub_f32_e32 v27, v27, v2
	v_mul_f32_e32 v24, 0x3e38aa3b, v24
	v_mul_f32_e32 v25, 0x3e38aa3b, v25
	v_mul_f32_e32 v26, 0x3e38aa3b, v26
	v_mul_f32_e32 v27, 0x3e38aa3b, v27
	v_exp_f32_e32 v24, v24
	v_exp_f32_e32 v25, v25
	v_exp_f32_e32 v26, v26
	v_exp_f32_e32 v27, v27
	v_cndmask_b32_e32 v24, 0, v24, vcc
	v_cndmask_b32_e64 v25, 0, v25, s[2:3]
	v_cndmask_b32_e64 v26, 0, v26, s[14:15]
	v_cndmask_b32_e64 v27, 0, v27, s[46:47]
	v_add_f32_e32 v3, v3, v24
	v_add_f32_e32 v3, v3, v25
	v_add_f32_e32 v3, v3, v26
	v_add_f32_e32 v3, v3, v27
	s_waitcnt lgkmcnt(8)
	v_cmp_lt_f32_e32 vcc, s75, v28
	v_cmp_lt_f32_e64 s[2:3], s75, v29
	v_cmp_lt_f32_e64 s[14:15], s75, v30
	v_cmp_lt_f32_e64 s[46:47], s75, v31
	v_sub_f32_e32 v28, v28, v2
	v_sub_f32_e32 v29, v29, v2
	v_sub_f32_e32 v30, v30, v2
	v_sub_f32_e32 v31, v31, v2
	v_mul_f32_e32 v28, 0x3e38aa3b, v28
	v_mul_f32_e32 v29, 0x3e38aa3b, v29
	v_mul_f32_e32 v30, 0x3e38aa3b, v30
	v_mul_f32_e32 v31, 0x3e38aa3b, v31
	v_exp_f32_e32 v28, v28
	v_exp_f32_e32 v29, v29
	v_exp_f32_e32 v30, v30
	v_exp_f32_e32 v31, v31
	v_cndmask_b32_e32 v28, 0, v28, vcc
	v_cndmask_b32_e64 v29, 0, v29, s[2:3]
	v_cndmask_b32_e64 v30, 0, v30, s[14:15]
	v_cndmask_b32_e64 v31, 0, v31, s[46:47]
	v_add_f32_e32 v3, v3, v28
	v_add_f32_e32 v3, v3, v29
	v_add_f32_e32 v3, v3, v30
	v_add_f32_e32 v3, v3, v31
	s_waitcnt lgkmcnt(6)
	v_cmp_lt_f32_e32 vcc, s75, v32
	v_cmp_lt_f32_e64 s[2:3], s75, v33
	v_cmp_lt_f32_e64 s[14:15], s75, v34
	v_cmp_lt_f32_e64 s[46:47], s75, v35
	v_sub_f32_e32 v32, v32, v2
	v_sub_f32_e32 v33, v33, v2
	v_sub_f32_e32 v34, v34, v2
	v_sub_f32_e32 v35, v35, v2
	v_mul_f32_e32 v32, 0x3e38aa3b, v32
	v_mul_f32_e32 v33, 0x3e38aa3b, v33
	v_mul_f32_e32 v34, 0x3e38aa3b, v34
	v_mul_f32_e32 v35, 0x3e38aa3b, v35
	v_exp_f32_e32 v32, v32
	v_exp_f32_e32 v33, v33
	v_exp_f32_e32 v34, v34
	v_exp_f32_e32 v35, v35
	v_cndmask_b32_e32 v32, 0, v32, vcc
	v_cndmask_b32_e64 v33, 0, v33, s[2:3]
	v_cndmask_b32_e64 v34, 0, v34, s[14:15]
	v_cndmask_b32_e64 v35, 0, v35, s[46:47]
	v_add_f32_e32 v3, v3, v32
	v_add_f32_e32 v3, v3, v33
	v_add_f32_e32 v3, v3, v34
	v_add_f32_e32 v3, v3, v35
	s_waitcnt lgkmcnt(4)
	v_cmp_lt_f32_e32 vcc, s75, v36
	v_cmp_lt_f32_e64 s[2:3], s75, v37
	v_cmp_lt_f32_e64 s[14:15], s75, v38
	v_cmp_lt_f32_e64 s[46:47], s75, v39
	v_sub_f32_e32 v36, v36, v2
	v_sub_f32_e32 v37, v37, v2
	v_sub_f32_e32 v38, v38, v2
	v_sub_f32_e32 v39, v39, v2
	v_mul_f32_e32 v36, 0x3e38aa3b, v36
	v_mul_f32_e32 v37, 0x3e38aa3b, v37
	v_mul_f32_e32 v38, 0x3e38aa3b, v38
	v_mul_f32_e32 v39, 0x3e38aa3b, v39
	v_exp_f32_e32 v36, v36
	v_exp_f32_e32 v37, v37
	v_exp_f32_e32 v38, v38
	v_exp_f32_e32 v39, v39
	v_cndmask_b32_e32 v36, 0, v36, vcc
	v_cndmask_b32_e64 v37, 0, v37, s[2:3]
	v_cndmask_b32_e64 v38, 0, v38, s[14:15]
	v_cndmask_b32_e64 v39, 0, v39, s[46:47]
	v_add_f32_e32 v3, v3, v36
	v_add_f32_e32 v3, v3, v37
	v_add_f32_e32 v3, v3, v38
	v_add_f32_e32 v3, v3, v39
	s_waitcnt lgkmcnt(2)
; __device__ __forceinline__ void dsa_item(const KP& p, int b, int tile, char* smem) {
;     ...
;     float sum = 0.f;
; #pragma unroll 4
;     for (int k = 0; k < 32; ++k) {
;       const int i = lane + 64 * k;
;       const float v = pbuf[i];
;       const float e = (v > -1e29f) ? __expf(v - mxh) : 0.f;
;       pbuf[i] = e;
;       sum += e;
;     }
	v_cmp_lt_f32_e32 vcc, s75, v40
	v_cmp_lt_f32_e64 s[2:3], s75, v41
	v_cmp_lt_f32_e64 s[14:15], s75, v42
	v_cmp_lt_f32_e64 s[46:47], s75, v43
	v_sub_f32_e32 v40, v40, v2
	v_sub_f32_e32 v41, v41, v2
	v_sub_f32_e32 v42, v42, v2
	v_sub_f32_e32 v43, v43, v2
	v_mul_f32_e32 v40, 0x3e38aa3b, v40
	v_mul_f32_e32 v41, 0x3e38aa3b, v41
	v_mul_f32_e32 v42, 0x3e38aa3b, v42
	v_mul_f32_e32 v43, 0x3e38aa3b, v43
	v_exp_f32_e32 v40, v40
	v_exp_f32_e32 v41, v41
	v_exp_f32_e32 v42, v42
	v_exp_f32_e32 v43, v43
	v_cndmask_b32_e32 v40, 0, v40, vcc
	v_cndmask_b32_e64 v41, 0, v41, s[2:3]
	v_cndmask_b32_e64 v42, 0, v42, s[14:15]
	v_cndmask_b32_e64 v43, 0, v43, s[46:47]
	v_add_f32_e32 v3, v3, v40
	v_add_f32_e32 v3, v3, v41
	v_add_f32_e32 v3, v3, v42
	v_add_f32_e32 v3, v3, v43
	s_waitcnt lgkmcnt(0)
	v_cmp_lt_f32_e32 vcc, s75, v44
	v_cmp_lt_f32_e64 s[2:3], s75, v45
	v_cmp_lt_f32_e64 s[14:15], s75, v46
	v_cmp_lt_f32_e64 s[46:47], s75, v47
	v_sub_f32_e32 v44, v44, v2
	v_sub_f32_e32 v45, v45, v2
	v_sub_f32_e32 v46, v46, v2
	v_sub_f32_e32 v47, v47, v2
	v_mul_f32_e32 v44, 0x3e38aa3b, v44
	v_mul_f32_e32 v45, 0x3e38aa3b, v45
	v_mul_f32_e32 v46, 0x3e38aa3b, v46
	v_mul_f32_e32 v47, 0x3e38aa3b, v47
	v_exp_f32_e32 v44, v44
	v_exp_f32_e32 v45, v45
	v_exp_f32_e32 v46, v46
	v_exp_f32_e32 v47, v47
	v_cndmask_b32_e32 v44, 0, v44, vcc
	v_cndmask_b32_e64 v45, 0, v45, s[2:3]
	v_cndmask_b32_e64 v46, 0, v46, s[14:15]
	v_cndmask_b32_e64 v47, 0, v47, s[46:47]
	v_add_f32_e32 v3, v3, v44
	v_add_f32_e32 v3, v3, v45
	v_add_f32_e32 v3, v3, v46
	v_add_f32_e32 v3, v3, v47
	s_branch .Lsm_done
.Lsm_full:
	s_waitcnt lgkmcnt(14)
	v_sub_f32_e32 v16, v16, v2
	v_sub_f32_e32 v17, v17, v2
	v_sub_f32_e32 v18, v18, v2
	v_sub_f32_e32 v19, v19, v2
	v_mul_f32_e32 v16, 0x3e38aa3b, v16
	v_mul_f32_e32 v17, 0x3e38aa3b, v17
	v_mul_f32_e32 v18, 0x3e38aa3b, v18
	v_mul_f32_e32 v19, 0x3e38aa3b, v19
	v_exp_f32_e32 v16, v16
	v_exp_f32_e32 v17, v17
	v_exp_f32_e32 v18, v18
	v_exp_f32_e32 v19, v19
	s_nop 0
	v_add_f32_e32 v3, v3, v16
	v_add_f32_e32 v3, v3, v17
	v_add_f32_e32 v3, v3, v18
	v_add_f32_e32 v3, v3, v19
	s_waitcnt lgkmcnt(12)
	v_sub_f32_e32 v20, v20, v2
	v_sub_f32_e32 v21, v21, v2
	v_sub_f32_e32 v22, v22, v2
	v_sub_f32_e32 v23, v23, v2
	v_mul_f32_e32 v20, 0x3e38aa3b, v20
	v_mul_f32_e32 v21, 0x3e38aa3b, v21
	v_mul_f32_e32 v22, 0x3e38aa3b, v22
	v_mul_f32_e32 v23, 0x3e38aa3b, v23
	v_exp_f32_e32 v20, v20
	v_exp_f32_e32 v21, v21
	v_exp_f32_e32 v22, v22
	v_exp_f32_e32 v23, v23
	s_nop 0
	v_add_f32_e32 v3, v3, v20
	v_add_f32_e32 v3, v3, v21
	v_add_f32_e32 v3, v3, v22
	v_add_f32_e32 v3, v3, v23
	s_waitcnt lgkmcnt(10)
	v_sub_f32_e32 v24, v24, v2
	v_sub_f32_e32 v25, v25, v2
	v_sub_f32_e32 v26, v26, v2
	v_sub_f32_e32 v27, v27, v2
	v_mul_f32_e32 v24, 0x3e38aa3b, v24
	v_mul_f32_e32 v25, 0x3e38aa3b, v25
	v_mul_f32_e32 v26, 0x3e38aa3b, v26
	v_mul_f32_e32 v27, 0x3e38aa3b, v27
	v_exp_f32_e32 v24, v24
	v_exp_f32_e32 v25, v25
	v_exp_f32_e32 v26, v26
	v_exp_f32_e32 v27, v27
	s_nop 0
	v_add_f32_e32 v3, v3, v24
	v_add_f32_e32 v3, v3, v25
	v_add_f32_e32 v3, v3, v26
	v_add_f32_e32 v3, v3, v27
	s_waitcnt lgkmcnt(8)
	v_sub_f32_e32 v28, v28, v2
	v_sub_f32_e32 v29, v29, v2
	v_sub_f32_e32 v30, v30, v2
	v_sub_f32_e32 v31, v31, v2
	v_mul_f32_e32 v28, 0x3e38aa3b, v28
	v_mul_f32_e32 v29, 0x3e38aa3b, v29
	v_mul_f32_e32 v30, 0x3e38aa3b, v30
	v_mul_f32_e32 v31, 0x3e38aa3b, v31
	v_exp_f32_e32 v28, v28
	v_exp_f32_e32 v29, v29
	v_exp_f32_e32 v30, v30
	v_exp_f32_e32 v31, v31
	s_nop 0
	v_add_f32_e32 v3, v3, v28
	v_add_f32_e32 v3, v3, v29
	v_add_f32_e32 v3, v3, v30
	v_add_f32_e32 v3, v3, v31
	s_waitcnt lgkmcnt(6)
	v_sub_f32_e32 v32, v32, v2
	v_sub_f32_e32 v33, v33, v2
	v_sub_f32_e32 v34, v34, v2
	v_sub_f32_e32 v35, v35, v2
	v_mul_f32_e32 v32, 0x3e38aa3b, v32
	v_mul_f32_e32 v33, 0x3e38aa3b, v33
	v_mul_f32_e32 v34, 0x3e38aa3b, v34
	v_mul_f32_e32 v35, 0x3e38aa3b, v35
	v_exp_f32_e32 v32, v32
	v_exp_f32_e32 v33, v33
	v_exp_f32_e32 v34, v34
	v_exp_f32_e32 v35, v35
	s_nop 0
	v_add_f32_e32 v3, v3, v32
	v_add_f32_e32 v3, v3, v33
	v_add_f32_e32 v3, v3, v34
	v_add_f32_e32 v3, v3, v35
	s_waitcnt lgkmcnt(4)
	v_sub_f32_e32 v36, v36, v2
	v_sub_f32_e32 v37, v37, v2
	v_sub_f32_e32 v38, v38, v2
	v_sub_f32_e32 v39, v39, v2
	v_mul_f32_e32 v36, 0x3e38aa3b, v36
	v_mul_f32_e32 v37, 0x3e38aa3b, v37
	v_mul_f32_e32 v38, 0x3e38aa3b, v38
	v_mul_f32_e32 v39, 0x3e38aa3b, v39
	v_exp_f32_e32 v36, v36
	v_exp_f32_e32 v37, v37
	v_exp_f32_e32 v38, v38
	v_exp_f32_e32 v39, v39
	s_nop 0
	v_add_f32_e32 v3, v3, v36
	v_add_f32_e32 v3, v3, v37
	v_add_f32_e32 v3, v3, v38
	v_add_f32_e32 v3, v3, v39
	s_waitcnt lgkmcnt(2)
	v_sub_f32_e32 v40, v40, v2
	v_sub_f32_e32 v41, v41, v2
	v_sub_f32_e32 v42, v42, v2
	v_sub_f32_e32 v43, v43, v2
	v_mul_f32_e32 v40, 0x3e38aa3b, v40
	v_mul_f32_e32 v41, 0x3e38aa3b, v41
	v_mul_f32_e32 v42, 0x3e38aa3b, v42
	v_mul_f32_e32 v43, 0x3e38aa3b, v43
	v_exp_f32_e32 v40, v40
	v_exp_f32_e32 v41, v41
	v_exp_f32_e32 v42, v42
	v_exp_f32_e32 v43, v43
	s_nop 0
	v_add_f32_e32 v3, v3, v40
	v_add_f32_e32 v3, v3, v41
	v_add_f32_e32 v3, v3, v42
	v_add_f32_e32 v3, v3, v43
	s_waitcnt lgkmcnt(0)
	v_sub_f32_e32 v44, v44, v2
	v_sub_f32_e32 v45, v45, v2
	v_sub_f32_e32 v46, v46, v2
	v_sub_f32_e32 v47, v47, v2
	v_mul_f32_e32 v44, 0x3e38aa3b, v44
	v_mul_f32_e32 v45, 0x3e38aa3b, v45
	v_mul_f32_e32 v46, 0x3e38aa3b, v46
	v_mul_f32_e32 v47, 0x3e38aa3b, v47
	v_exp_f32_e32 v44, v44
	v_exp_f32_e32 v45, v45
	v_exp_f32_e32 v46, v46
	v_exp_f32_e32 v47, v47
	s_nop 0
	v_add_f32_e32 v3, v3, v44
	v_add_f32_e32 v3, v3, v45
	v_add_f32_e32 v3, v3, v46
	v_add_f32_e32 v3, v3, v47
